# NA: K/V LDS-DMA ring in the grid-tile loop plus epilogue gate loads issued at the top of the last grid tile (on top of GQA+MLA ping-pong); later code padded to the same placement
# speedup vs baseline: 1.0018x; 1.0018x over previous
.Lna_nodma:
	s_cmp_eq_u32 s39, 11
	s_cbranch_scc0 .Lna_nogate
	s_lshl_b32 s8, s92, 7
	s_add_u32 s8, s34, s8
	s_addc_u32 s9, s35, 0
	s_add_u32 s8, s8, 0x1800
	s_addc_u32 s9, s9, 0
	v_lshl_add_u32 v188, v108, 1, v120
	v_add_u32_e32 v188, v188, v122
	global_load_ushort v222, v188, s[8:9] offset:0
	global_load_ushort v223, v188, s[8:9] offset:64
	s_add_u32 s8, s8, 0x2000
	s_addc_u32 s9, s9, 0
	global_load_ushort v224, v188, s[8:9] offset:0
	global_load_ushort v225, v188, s[8:9] offset:64
	s_add_u32 s8, s8, 0x2000
	s_addc_u32 s9, s9, 0
	global_load_ushort v226, v188, s[8:9] offset:0
	global_load_ushort v227, v188, s[8:9] offset:64
	s_add_u32 s8, s8, 0x2000
	s_addc_u32 s9, s9, 0
	global_load_ushort v228, v188, s[8:9] offset:0
	global_load_ushort v229, v188, s[8:9] offset:64
	s_add_u32 s8, s8, 0xa000
	s_addc_u32 s9, s9, 0
	global_load_ushort v230, v188, s[8:9] offset:0
	global_load_ushort v231, v188, s[8:9] offset:64
	s_add_u32 s8, s8, 0x2000
	s_addc_u32 s9, s9, 0
	global_load_ushort v232, v188, s[8:9] offset:0
	global_load_ushort v233, v188, s[8:9] offset:64
	s_add_u32 s8, s8, 0x2000
	s_addc_u32 s9, s9, 0
	global_load_ushort v234, v188, s[8:9] offset:0
	global_load_ushort v235, v188, s[8:9] offset:64
	s_add_u32 s8, s8, 0x2000
	s_addc_u32 s9, s9, 0
	global_load_ushort v236, v188, s[8:9] offset:0
	global_load_ushort v237, v188, s[8:9] offset:64
	s_add_u32 s8, s8, 0xa000
	s_addc_u32 s9, s9, 0
	global_load_ushort v238, v188, s[8:9] offset:0
	global_load_ushort v239, v188, s[8:9] offset:64
	s_add_u32 s8, s8, 0x2000
	s_addc_u32 s9, s9, 0
	global_load_ushort v240, v188, s[8:9] offset:0
	global_load_ushort v241, v188, s[8:9] offset:64
	s_add_u32 s8, s8, 0x2000
	s_addc_u32 s9, s9, 0
	global_load_ushort v242, v188, s[8:9] offset:0
	global_load_ushort v243, v188, s[8:9] offset:64
	s_add_u32 s8, s8, 0x2000
	s_addc_u32 s9, s9, 0
	global_load_ushort v244, v188, s[8:9] offset:0
	global_load_ushort v245, v188, s[8:9] offset:64
	s_add_u32 s8, s8, 0xa000
	s_addc_u32 s9, s9, 0
	global_load_ushort v246, v188, s[8:9] offset:0
	global_load_ushort v247, v188, s[8:9] offset:64
	s_add_u32 s8, s8, 0x2000
	s_addc_u32 s9, s9, 0
	global_load_ushort v248, v188, s[8:9] offset:0
	global_load_ushort v249, v188, s[8:9] offset:64
	s_add_u32 s8, s8, 0x2000
	s_addc_u32 s9, s9, 0
	global_load_ushort v250, v188, s[8:9] offset:0
	global_load_ushort v251, v188, s[8:9] offset:64
	s_add_u32 s8, s8, 0x2000
	s_addc_u32 s9, s9, 0
	global_load_ushort v252, v188, s[8:9] offset:0
	global_load_ushort v253, v188, s[8:9] offset:64

.LBB0_249:
	s_or_b64 exec, exec, s[74:75]
	s_sub_i32 s8, s38, s39
	s_cmp_eq_u32 s8, 1
	s_cbranch_scc1 .LBB0_237
	s_cmp_gt_u32 s8, 3
	s_cbranch_scc1 .Lna_w4
	s_cmp_eq_u32 s8, 3
	s_cbranch_scc1 .Lna_w2
	s_waitcnt vmcnt(0)
	s_branch .LBB0_237

.LBB0_256:
	s_lshl_b32 s8, s92, 6
	s_lshl_b32 s8, s8, 1
	s_add_u32 s8, s34, s8
	s_addc_u32 s9, s35, 0
	s_add_u32 s74, s8, 0x1800
	s_addc_u32 s75, s9, 0
	s_and_b64 vcc, exec, s[6:7]
	s_cbranch_vccz .LBB0_260
	s_and_saveexec_b64 s[8:9], s[76:77]
	ds_write_b32 v134, v128 offset:32768
	s_or_b64 exec, exec, s[8:9]
	s_waitcnt lgkmcnt(0)
	v_add_u32_e32 v105, v109, v119
	ds_read_b128 v[68:71], v105 offset:32768
	ds_read_b128 v[72:75], v105 offset:32800
	ds_read_b128 v[76:79], v105 offset:32832
	ds_read_b128 v[80:83], v105 offset:32864
	v_lshl_add_u32 v104, v108, 1, v120
	v_add_u32_e32 v104, v104, v122
	s_waitcnt lgkmcnt(0)
	v_rcp_f32_e32 v84, v68
	v_rcp_f32_e32 v85, v69
	v_rcp_f32_e32 v86, v70
	v_rcp_f32_e32 v87, v71
	v_rcp_f32_e32 v88, v72
	v_rcp_f32_e32 v89, v73
	v_rcp_f32_e32 v90, v74
	v_rcp_f32_e32 v91, v75
	v_rcp_f32_e32 v92, v76
	v_rcp_f32_e32 v93, v77
	v_rcp_f32_e32 v94, v78
	v_rcp_f32_e32 v95, v79
	v_rcp_f32_e32 v96, v80
	v_rcp_f32_e32 v97, v81
	v_rcp_f32_e32 v98, v82
	v_rcp_f32_e32 v99, v83
	s_waitcnt vmcnt(30)
	v_lshlrev_b32_e32 v222, 16, v222
	v_lshlrev_b32_e32 v223, 16, v223
	v_mul_f32_e32 v100, 0xbfb8aa3b, v222
	v_mul_f32_e32 v101, 0xbfb8aa3b, v223
	v_exp_f32_e32 v100, v100
	v_exp_f32_e32 v101, v101
	v_mul_f32_e32 v102, v2, v84
	v_mul_f32_e32 v103, v18, v84
	v_add_f32_e32 v100, 1.0, v100
	v_add_f32_e32 v101, 1.0, v101
	v_rcp_f32_e32 v100, v100
	v_rcp_f32_e32 v101, v101
	s_nop 0
	v_mul_f32_e32 v222, v100, v222
	v_mul_f32_e32 v223, v101, v223
	v_mul_f32_e32 v222, v102, v222
	v_mul_f32_e32 v223, v103, v223
	v_cvt_pk_bf16_f32 v222, v222, v222
	v_cvt_pk_bf16_f32 v223, v223, v223
	s_waitcnt vmcnt(28)
	v_lshlrev_b32_e32 v224, 16, v224
	v_lshlrev_b32_e32 v225, 16, v225
	v_mul_f32_e32 v100, 0xbfb8aa3b, v224
	v_mul_f32_e32 v101, 0xbfb8aa3b, v225
	v_exp_f32_e32 v100, v100
	v_exp_f32_e32 v101, v101
	v_mul_f32_e32 v102, v3, v85
	v_mul_f32_e32 v103, v19, v85
	v_add_f32_e32 v100, 1.0, v100
	v_add_f32_e32 v101, 1.0, v101
	v_rcp_f32_e32 v100, v100
	v_rcp_f32_e32 v101, v101
	s_nop 0
	v_mul_f32_e32 v224, v100, v224
	v_mul_f32_e32 v225, v101, v225
	v_mul_f32_e32 v224, v102, v224
	v_mul_f32_e32 v225, v103, v225
	v_cvt_pk_bf16_f32 v224, v224, v224
	v_cvt_pk_bf16_f32 v225, v225, v225
	s_waitcnt vmcnt(26)
	v_lshlrev_b32_e32 v226, 16, v226
	v_lshlrev_b32_e32 v227, 16, v227
	v_mul_f32_e32 v100, 0xbfb8aa3b, v226
	v_mul_f32_e32 v101, 0xbfb8aa3b, v227
	v_exp_f32_e32 v100, v100
	v_exp_f32_e32 v101, v101
	v_mul_f32_e32 v102, v4, v86
	v_mul_f32_e32 v103, v20, v86
	v_add_f32_e32 v100, 1.0, v100
	v_add_f32_e32 v101, 1.0, v101
	v_rcp_f32_e32 v100, v100
	v_rcp_f32_e32 v101, v101
	s_nop 0
	v_mul_f32_e32 v226, v100, v226
	v_mul_f32_e32 v227, v101, v227
	v_mul_f32_e32 v226, v102, v226
	v_mul_f32_e32 v227, v103, v227
	v_cvt_pk_bf16_f32 v226, v226, v226
	v_cvt_pk_bf16_f32 v227, v227, v227
	s_waitcnt vmcnt(24)
	v_lshlrev_b32_e32 v228, 16, v228
	v_lshlrev_b32_e32 v229, 16, v229
	v_mul_f32_e32 v100, 0xbfb8aa3b, v228
	v_mul_f32_e32 v101, 0xbfb8aa3b, v229
	v_exp_f32_e32 v100, v100
	v_exp_f32_e32 v101, v101
	v_mul_f32_e32 v102, v5, v87
	v_mul_f32_e32 v103, v21, v87
	v_add_f32_e32 v100, 1.0, v100
	v_add_f32_e32 v101, 1.0, v101
	v_rcp_f32_e32 v100, v100
	v_rcp_f32_e32 v101, v101
	s_nop 0
	v_mul_f32_e32 v228, v100, v228
	v_mul_f32_e32 v229, v101, v229
	v_mul_f32_e32 v228, v102, v228
	v_mul_f32_e32 v229, v103, v229
	v_cvt_pk_bf16_f32 v228, v228, v228
	v_cvt_pk_bf16_f32 v229, v229, v229
	s_waitcnt vmcnt(22)
	v_lshlrev_b32_e32 v230, 16, v230
	v_lshlrev_b32_e32 v231, 16, v231
	v_mul_f32_e32 v100, 0xbfb8aa3b, v230
	v_mul_f32_e32 v101, 0xbfb8aa3b, v231
	v_exp_f32_e32 v100, v100
	v_exp_f32_e32 v101, v101
	v_mul_f32_e32 v102, v6, v88
	v_mul_f32_e32 v103, v22, v88
	v_add_f32_e32 v100, 1.0, v100
	v_add_f32_e32 v101, 1.0, v101
	v_rcp_f32_e32 v100, v100
	v_rcp_f32_e32 v101, v101
	s_nop 0
	v_mul_f32_e32 v230, v100, v230
	v_mul_f32_e32 v231, v101, v231
	v_mul_f32_e32 v230, v102, v230
	v_mul_f32_e32 v231, v103, v231
	v_cvt_pk_bf16_f32 v230, v230, v230
	v_cvt_pk_bf16_f32 v231, v231, v231
	s_waitcnt vmcnt(20)
	v_lshlrev_b32_e32 v232, 16, v232
	v_lshlrev_b32_e32 v233, 16, v233
	v_mul_f32_e32 v100, 0xbfb8aa3b, v232
	v_mul_f32_e32 v101, 0xbfb8aa3b, v233
	v_exp_f32_e32 v100, v100
	v_exp_f32_e32 v101, v101
	v_mul_f32_e32 v102, v7, v89
	v_mul_f32_e32 v103, v23, v89
	v_add_f32_e32 v100, 1.0, v100
	v_add_f32_e32 v101, 1.0, v101
	v_rcp_f32_e32 v100, v100
	v_rcp_f32_e32 v101, v101
	s_nop 0
	v_mul_f32_e32 v232, v100, v232
	v_mul_f32_e32 v233, v101, v233
	v_mul_f32_e32 v232, v102, v232
	v_mul_f32_e32 v233, v103, v233
	v_cvt_pk_bf16_f32 v232, v232, v232
	v_cvt_pk_bf16_f32 v233, v233, v233
	s_waitcnt vmcnt(18)
	v_lshlrev_b32_e32 v234, 16, v234
	v_lshlrev_b32_e32 v235, 16, v235
	v_mul_f32_e32 v100, 0xbfb8aa3b, v234
	v_mul_f32_e32 v101, 0xbfb8aa3b, v235
	v_exp_f32_e32 v100, v100
	v_exp_f32_e32 v101, v101
	v_mul_f32_e32 v102, v8, v90
	v_mul_f32_e32 v103, v24, v90
	v_add_f32_e32 v100, 1.0, v100
	v_add_f32_e32 v101, 1.0, v101
	v_rcp_f32_e32 v100, v100
	v_rcp_f32_e32 v101, v101
	s_nop 0
	v_mul_f32_e32 v234, v100, v234
	v_mul_f32_e32 v235, v101, v235
	v_mul_f32_e32 v234, v102, v234
	v_mul_f32_e32 v235, v103, v235
	v_cvt_pk_bf16_f32 v234, v234, v234
	v_cvt_pk_bf16_f32 v235, v235, v235
	s_waitcnt vmcnt(16)
	v_lshlrev_b32_e32 v236, 16, v236
	v_lshlrev_b32_e32 v237, 16, v237
	v_mul_f32_e32 v100, 0xbfb8aa3b, v236
	v_mul_f32_e32 v101, 0xbfb8aa3b, v237
	v_exp_f32_e32 v100, v100
	v_exp_f32_e32 v101, v101
	v_mul_f32_e32 v102, v9, v91
	v_mul_f32_e32 v103, v25, v91
	v_add_f32_e32 v100, 1.0, v100
	v_add_f32_e32 v101, 1.0, v101
	v_rcp_f32_e32 v100, v100
	v_rcp_f32_e32 v101, v101
	s_nop 0
	v_mul_f32_e32 v236, v100, v236
	v_mul_f32_e32 v237, v101, v237
	v_mul_f32_e32 v236, v102, v236
	v_mul_f32_e32 v237, v103, v237
	v_cvt_pk_bf16_f32 v236, v236, v236
	v_cvt_pk_bf16_f32 v237, v237, v237
	s_waitcnt vmcnt(14)
	v_lshlrev_b32_e32 v238, 16, v238
	v_lshlrev_b32_e32 v239, 16, v239
	v_mul_f32_e32 v100, 0xbfb8aa3b, v238
	v_mul_f32_e32 v101, 0xbfb8aa3b, v239
	v_exp_f32_e32 v100, v100
	v_exp_f32_e32 v101, v101
	v_mul_f32_e32 v102, v10, v92
	v_mul_f32_e32 v103, v26, v92
	v_add_f32_e32 v100, 1.0, v100
	v_add_f32_e32 v101, 1.0, v101
	v_rcp_f32_e32 v100, v100
	v_rcp_f32_e32 v101, v101
	s_nop 0
	v_mul_f32_e32 v238, v100, v238
	v_mul_f32_e32 v239, v101, v239
	v_mul_f32_e32 v238, v102, v238
	v_mul_f32_e32 v239, v103, v239
	v_cvt_pk_bf16_f32 v238, v238, v238
	v_cvt_pk_bf16_f32 v239, v239, v239
	s_waitcnt vmcnt(12)
	v_lshlrev_b32_e32 v240, 16, v240
	v_lshlrev_b32_e32 v241, 16, v241
	v_mul_f32_e32 v100, 0xbfb8aa3b, v240
	v_mul_f32_e32 v101, 0xbfb8aa3b, v241
	v_exp_f32_e32 v100, v100
	v_exp_f32_e32 v101, v101
	v_mul_f32_e32 v102, v11, v93
	v_mul_f32_e32 v103, v27, v93
	v_add_f32_e32 v100, 1.0, v100
	v_add_f32_e32 v101, 1.0, v101
	v_rcp_f32_e32 v100, v100
	v_rcp_f32_e32 v101, v101
	s_nop 0
	v_mul_f32_e32 v240, v100, v240
	v_mul_f32_e32 v241, v101, v241
	v_mul_f32_e32 v240, v102, v240
	v_mul_f32_e32 v241, v103, v241
	v_cvt_pk_bf16_f32 v240, v240, v240
	v_cvt_pk_bf16_f32 v241, v241, v241
	s_waitcnt vmcnt(10)
	v_lshlrev_b32_e32 v242, 16, v242
	v_lshlrev_b32_e32 v243, 16, v243
	v_mul_f32_e32 v100, 0xbfb8aa3b, v242
	v_mul_f32_e32 v101, 0xbfb8aa3b, v243
	v_exp_f32_e32 v100, v100
	v_exp_f32_e32 v101, v101
	v_mul_f32_e32 v102, v12, v94
	v_mul_f32_e32 v103, v28, v94
	v_add_f32_e32 v100, 1.0, v100
	v_add_f32_e32 v101, 1.0, v101
	v_rcp_f32_e32 v100, v100
	v_rcp_f32_e32 v101, v101
	s_nop 0
	v_mul_f32_e32 v242, v100, v242
	v_mul_f32_e32 v243, v101, v243
	v_mul_f32_e32 v242, v102, v242
	v_mul_f32_e32 v243, v103, v243
	v_cvt_pk_bf16_f32 v242, v242, v242
	v_cvt_pk_bf16_f32 v243, v243, v243
	s_waitcnt vmcnt(8)
	v_lshlrev_b32_e32 v244, 16, v244
	v_lshlrev_b32_e32 v245, 16, v245
	v_mul_f32_e32 v100, 0xbfb8aa3b, v244
	v_mul_f32_e32 v101, 0xbfb8aa3b, v245
	v_exp_f32_e32 v100, v100
	v_exp_f32_e32 v101, v101
	v_mul_f32_e32 v102, v13, v95
	v_mul_f32_e32 v103, v29, v95
	v_add_f32_e32 v100, 1.0, v100
	v_add_f32_e32 v101, 1.0, v101
	v_rcp_f32_e32 v100, v100
	v_rcp_f32_e32 v101, v101
	s_nop 0
	v_mul_f32_e32 v244, v100, v244
	v_mul_f32_e32 v245, v101, v245
	v_mul_f32_e32 v244, v102, v244
	v_mul_f32_e32 v245, v103, v245
	v_cvt_pk_bf16_f32 v244, v244, v244
	v_cvt_pk_bf16_f32 v245, v245, v245
	s_waitcnt vmcnt(6)
	v_lshlrev_b32_e32 v246, 16, v246
	v_lshlrev_b32_e32 v247, 16, v247
	v_mul_f32_e32 v100, 0xbfb8aa3b, v246
	v_mul_f32_e32 v101, 0xbfb8aa3b, v247
	v_exp_f32_e32 v100, v100
	v_exp_f32_e32 v101, v101
	v_mul_f32_e32 v102, v14, v96
	v_mul_f32_e32 v103, v30, v96
	v_add_f32_e32 v100, 1.0, v100
	v_add_f32_e32 v101, 1.0, v101
	v_rcp_f32_e32 v100, v100
	v_rcp_f32_e32 v101, v101
	s_nop 0
	v_mul_f32_e32 v246, v100, v246
	v_mul_f32_e32 v247, v101, v247
	v_mul_f32_e32 v246, v102, v246
	v_mul_f32_e32 v247, v103, v247
	v_cvt_pk_bf16_f32 v246, v246, v246
	v_cvt_pk_bf16_f32 v247, v247, v247
	s_waitcnt vmcnt(4)
	v_lshlrev_b32_e32 v248, 16, v248
	v_lshlrev_b32_e32 v249, 16, v249
	v_mul_f32_e32 v100, 0xbfb8aa3b, v248
	v_mul_f32_e32 v101, 0xbfb8aa3b, v249
	v_exp_f32_e32 v100, v100
	v_exp_f32_e32 v101, v101
	v_mul_f32_e32 v102, v15, v97
	v_mul_f32_e32 v103, v31, v97
	v_add_f32_e32 v100, 1.0, v100
	v_add_f32_e32 v101, 1.0, v101
	v_rcp_f32_e32 v100, v100
	v_rcp_f32_e32 v101, v101
	s_nop 0
	v_mul_f32_e32 v248, v100, v248
	v_mul_f32_e32 v249, v101, v249
	v_mul_f32_e32 v248, v102, v248
	v_mul_f32_e32 v249, v103, v249
	v_cvt_pk_bf16_f32 v248, v248, v248
	v_cvt_pk_bf16_f32 v249, v249, v249
	s_waitcnt vmcnt(2)
	v_lshlrev_b32_e32 v250, 16, v250
	v_lshlrev_b32_e32 v251, 16, v251
	v_mul_f32_e32 v100, 0xbfb8aa3b, v250
	v_mul_f32_e32 v101, 0xbfb8aa3b, v251
	v_exp_f32_e32 v100, v100
	v_exp_f32_e32 v101, v101
	v_mul_f32_e32 v102, v16, v98
	v_mul_f32_e32 v103, v32, v98
	v_add_f32_e32 v100, 1.0, v100
	v_add_f32_e32 v101, 1.0, v101
	v_rcp_f32_e32 v100, v100
	v_rcp_f32_e32 v101, v101
	s_nop 0
	v_mul_f32_e32 v250, v100, v250
	v_mul_f32_e32 v251, v101, v251
	v_mul_f32_e32 v250, v102, v250
	v_mul_f32_e32 v251, v103, v251
	v_cvt_pk_bf16_f32 v250, v250, v250
	v_cvt_pk_bf16_f32 v251, v251, v251
	s_waitcnt vmcnt(0)
	v_lshlrev_b32_e32 v252, 16, v252
	v_lshlrev_b32_e32 v253, 16, v253
	v_mul_f32_e32 v100, 0xbfb8aa3b, v252
	v_mul_f32_e32 v101, 0xbfb8aa3b, v253
	v_exp_f32_e32 v100, v100
	v_exp_f32_e32 v101, v101
	v_mul_f32_e32 v102, v17, v99
	v_mul_f32_e32 v103, v33, v99
	v_add_f32_e32 v100, 1.0, v100
	v_add_f32_e32 v101, 1.0, v101
	v_rcp_f32_e32 v100, v100
	v_rcp_f32_e32 v101, v101
	s_nop 0
	v_mul_f32_e32 v252, v100, v252
	v_mul_f32_e32 v253, v101, v253
	v_mul_f32_e32 v252, v102, v252
	v_mul_f32_e32 v253, v103, v253
	v_cvt_pk_bf16_f32 v252, v252, v252
	v_cvt_pk_bf16_f32 v253, v253, v253
	s_mov_b32 s8, s74
	s_mov_b32 s9, s75
	global_store_short v104, v222, s[8:9] offset:0
	global_store_short v104, v223, s[8:9] offset:64
	s_add_u32 s8, s8, 0x2000
	s_addc_u32 s9, s9, 0
	global_store_short v104, v224, s[8:9] offset:0
	global_store_short v104, v225, s[8:9] offset:64
	s_add_u32 s8, s8, 0x2000
	s_addc_u32 s9, s9, 0
	global_store_short v104, v226, s[8:9] offset:0
	global_store_short v104, v227, s[8:9] offset:64
	s_add_u32 s8, s8, 0x2000
	s_addc_u32 s9, s9, 0
	global_store_short v104, v228, s[8:9] offset:0
	global_store_short v104, v229, s[8:9] offset:64
	s_add_u32 s8, s8, 0xa000
	s_addc_u32 s9, s9, 0
	global_store_short v104, v230, s[8:9] offset:0
	global_store_short v104, v231, s[8:9] offset:64
	s_add_u32 s8, s8, 0x2000
	s_addc_u32 s9, s9, 0
	global_store_short v104, v232, s[8:9] offset:0
	global_store_short v104, v233, s[8:9] offset:64
	s_add_u32 s8, s8, 0x2000
	s_addc_u32 s9, s9, 0
	global_store_short v104, v234, s[8:9] offset:0
	global_store_short v104, v235, s[8:9] offset:64
	s_add_u32 s8, s8, 0x2000
	s_addc_u32 s9, s9, 0
	global_store_short v104, v236, s[8:9] offset:0
	global_store_short v104, v237, s[8:9] offset:64
	s_add_u32 s8, s8, 0xa000
	s_addc_u32 s9, s9, 0
	global_store_short v104, v238, s[8:9] offset:0
	global_store_short v104, v239, s[8:9] offset:64
	s_add_u32 s8, s8, 0x2000
	s_addc_u32 s9, s9, 0
	global_store_short v104, v240, s[8:9] offset:0
	global_store_short v104, v241, s[8:9] offset:64
	s_add_u32 s8, s8, 0x2000
	s_addc_u32 s9, s9, 0
	global_store_short v104, v242, s[8:9] offset:0
	global_store_short v104, v243, s[8:9] offset:64
	s_add_u32 s8, s8, 0x2000
	s_addc_u32 s9, s9, 0
	global_store_short v104, v244, s[8:9] offset:0
	global_store_short v104, v245, s[8:9] offset:64
	s_add_u32 s8, s8, 0xa000
	s_addc_u32 s9, s9, 0
	global_store_short v104, v246, s[8:9] offset:0
	global_store_short v104, v247, s[8:9] offset:64
	s_add_u32 s8, s8, 0x2000
	s_addc_u32 s9, s9, 0
	global_store_short v104, v248, s[8:9] offset:0
	global_store_short v104, v249, s[8:9] offset:64
	s_add_u32 s8, s8, 0x2000
	s_addc_u32 s9, s9, 0
	global_store_short v104, v250, s[8:9] offset:0
	global_store_short v104, v251, s[8:9] offset:64
	s_add_u32 s8, s8, 0x2000
	s_addc_u32 s9, s9, 0
	global_store_short v104, v252, s[8:9] offset:0
	global_store_short v104, v253, s[8:9] offset:64
	s_branch .LBB0_164

.LBB0_267:
	s_mov_b64 s[4:5], -1
	s_nop 0
	s_nop 0
	s_nop 0
	s_nop 0
	s_nop 0
	s_nop 0
	s_nop 0
	s_nop 0
	s_nop 0
	s_nop 0
	s_nop 0
	s_nop 0
	s_nop 0
	s_nop 0
	s_nop 0
	s_nop 0
	s_nop 0
	s_nop 0
	s_nop 0
	s_nop 0
	s_nop 0
	s_nop 0
	s_nop 0
	s_nop 0
	s_nop 0
	s_nop 0
	s_nop 0
	s_nop 0
	s_nop 0
	s_nop 0
	s_nop 0
	s_nop 0
	s_nop 0
	s_nop 0
	s_nop 0
	s_nop 0
	s_nop 0
	s_nop 0
	s_nop 0
	s_nop 0
	s_nop 0
	s_nop 0
	s_nop 0
	s_nop 0
	s_nop 0
	s_nop 0
	s_nop 0
	s_nop 0
	s_nop 0
	s_nop 0
	s_nop 0
	s_nop 0
	s_nop 0
